# SwiGLU epilogue: paired (x * -log2e) and (1 + e) steps as packed f32 ops, bit-identical
# speedup vs baseline: 1.0036x; 1.0036x over previous
.LBB0_815:
	v_mov_b32_e32 v244, 0xbfb8aa3b
	v_mov_b32_e32 v245, 0xbfb8aa3b
	v_mov_b32_e32 v246, 1.0
	v_mov_b32_e32 v247, 1.0
	v_lshl_add_u32 v150, s49, 10, v146
	ds_read2_b32 v[142:143], v150 offset1:16
	v_lshl_or_b32 v140, s31, 7, v147
	v_lshl_add_u32 v149, s30, 8, v144
	v_ashrrev_i32_e32 v141, 31, v140
	s_movk_i32 s15, 0x1600
	s_waitcnt lgkmcnt(0)
	v_pk_mul_f32 v[126:127], v[126:127], v[142:143] op_sel_hi:[1,0]
	v_pk_mul_f32 v[122:123], v[122:123], v[142:143] op_sel_hi:[1,0]
	v_mul_f32_e32 v151, 0xbfb8aa3b, v126
	v_exp_f32_e32 v151, v151
	v_pk_mul_f32 v[124:125], v[124:125], v[142:143] op_sel_hi:[1,0]
	v_pk_mul_f32 v[118:119], v[118:119], v[142:143] op_sel_hi:[1,0]
	v_pk_mul_f32 v[114:115], v[114:115], v[142:143] op_sel_hi:[1,0]
	v_add_f32_e32 v151, 1.0, v151
	v_rcp_f32_e32 v152, v151
	v_mul_f32_e32 v151, 0xbfb8aa3b, v127
	v_exp_f32_e32 v151, v151
	v_pk_mul_f32 v[116:117], v[116:117], v[142:143] op_sel_hi:[1,0]
	s_andn2_b64 vcc, exec, s[34:35]
	v_add_f32_e32 v151, 1.0, v151
	v_rcp_f32_e32 v153, v151
	s_nop 0
	v_pk_mul_f32 v[126:127], v[126:127], v[152:153]
	s_nop 0
	v_pk_mul_f32 v[122:123], v[122:123], v[126:127]
	v_pk_mul_f32 v[126:127], v[128:129], v[142:143] op_sel_hi:[1,0]
	s_nop 0
	v_pk_mul_f32 v[128:129], v[126:127], v[244:245]
	v_exp_f32_e32 v128, v128
	v_exp_f32_e32 v129, v129
	s_nop 0
	v_pk_add_f32 v[128:129], v[128:129], v[246:247]
	v_rcp_f32_e32 v128, v128
	v_rcp_f32_e32 v129, v129
	s_nop 0
	v_pk_mul_f32 v[126:127], v[126:127], v[128:129]
	s_nop 0
	v_pk_mul_f32 v[124:125], v[124:125], v[126:127]
	v_pk_mul_f32 v[126:127], v[118:119], v[244:245]
	v_exp_f32_e32 v126, v126
	v_exp_f32_e32 v127, v127
	s_nop 0
	v_pk_add_f32 v[126:127], v[126:127], v[246:247]
	v_rcp_f32_e32 v126, v126
	v_rcp_f32_e32 v127, v127
	s_nop 0
	v_pk_mul_f32 v[118:119], v[118:119], v[126:127]
	s_nop 0
	v_pk_mul_f32 v[114:115], v[114:115], v[118:119]
	v_pk_mul_f32 v[118:119], v[120:121], v[142:143] op_sel_hi:[1,0]
	s_nop 0
	v_pk_mul_f32 v[120:121], v[118:119], v[244:245]
	v_exp_f32_e32 v120, v120
	v_exp_f32_e32 v121, v121
	s_nop 0
	v_pk_add_f32 v[120:121], v[120:121], v[246:247]
	v_rcp_f32_e32 v120, v120
	v_rcp_f32_e32 v121, v121
	s_nop 0
	v_pk_mul_f32 v[118:119], v[118:119], v[120:121]
	s_nop 0
	v_pk_mul_f32 v[116:117], v[116:117], v[118:119]
	v_cvt_pk_bf16_f32 v120, v114, v115
	v_mov_b64_e32 v[114:115], s[10:11]
	v_cvt_pk_bf16_f32 v118, v122, v123
	v_cvt_pk_bf16_f32 v121, v116, v117
	v_mad_i64_i32 v[122:123], s[30:31], v149, s15, v[114:115]
	v_lshlrev_b64 v[116:117], 1, v[140:141]
	v_cvt_pk_bf16_f32 v119, v124, v125
	v_lshl_add_u64 v[122:123], v[122:123], 0, v[116:117]
	global_store_dwordx4 v[122:123], v[118:121], off sc0 sc1
	s_nop 1
	v_mov_b32_e32 v118, v143
	v_pk_mul_f32 v[110:111], v[110:111], v[118:119] op_sel_hi:[1,0]
	s_nop 0
	v_mul_f32_e32 v119, 0xbfb8aa3b, v110
	v_exp_f32_e32 v119, v119
	s_nop 0
	v_add_f32_e32 v119, 1.0, v119
	v_rcp_f32_e32 v120, v119
	v_pk_mul_f32 v[106:107], v[106:107], v[118:119] op_sel_hi:[1,0]
	v_mul_f32_e32 v119, 0xbfb8aa3b, v111
	v_exp_f32_e32 v119, v119
	s_nop 0
	v_add_f32_e32 v119, 1.0, v119
	v_rcp_f32_e32 v121, v119
	v_pk_mul_f32 v[108:109], v[108:109], v[118:119] op_sel_hi:[1,0]
	v_pk_mul_f32 v[102:103], v[102:103], v[118:119] op_sel_hi:[1,0]
	v_pk_mul_f32 v[98:99], v[98:99], v[118:119] op_sel_hi:[1,0]
	v_pk_mul_f32 v[110:111], v[110:111], v[120:121]
	v_pk_mul_f32 v[100:101], v[100:101], v[118:119] op_sel_hi:[1,0]
	v_pk_mul_f32 v[106:107], v[106:107], v[110:111]
	v_pk_mul_f32 v[110:111], v[112:113], v[118:119] op_sel_hi:[1,0]
	s_nop 0
	v_pk_mul_f32 v[112:113], v[110:111], v[244:245]
	v_exp_f32_e32 v112, v112
	v_exp_f32_e32 v113, v113
	s_nop 0
	v_pk_add_f32 v[112:113], v[112:113], v[246:247]
	v_rcp_f32_e32 v112, v112
	v_rcp_f32_e32 v113, v113
	s_nop 0
	v_pk_mul_f32 v[110:111], v[110:111], v[112:113]
	s_nop 0
	v_pk_mul_f32 v[108:109], v[108:109], v[110:111]
	v_pk_mul_f32 v[110:111], v[102:103], v[244:245]
	v_exp_f32_e32 v110, v110
	v_exp_f32_e32 v111, v111
	s_nop 0
	v_pk_add_f32 v[110:111], v[110:111], v[246:247]
	v_rcp_f32_e32 v110, v110
	v_rcp_f32_e32 v111, v111
	s_nop 0
	v_pk_mul_f32 v[102:103], v[102:103], v[110:111]
	s_nop 0
	v_pk_mul_f32 v[102:103], v[98:99], v[102:103]
	v_pk_mul_f32 v[98:99], v[104:105], v[118:119] op_sel_hi:[1,0]
	v_or_b32_e32 v110, 16, v149
	v_pk_mul_f32 v[104:105], v[98:99], v[244:245]
	v_exp_f32_e32 v104, v104
	v_exp_f32_e32 v105, v105
	s_nop 0
	v_pk_add_f32 v[104:105], v[104:105], v[246:247]
	v_rcp_f32_e32 v104, v104
	v_rcp_f32_e32 v105, v105
	s_nop 0
	v_pk_mul_f32 v[98:99], v[98:99], v[104:105]
	s_nop 0
	v_pk_mul_f32 v[104:105], v[100:101], v[98:99]
	v_cvt_pk_bf16_f32 v100, v102, v103
	v_mad_i64_i32 v[102:103], s[30:31], v110, s15, v[114:115]
	v_cvt_pk_bf16_f32 v98, v106, v107
	v_cvt_pk_bf16_f32 v99, v108, v109
	v_cvt_pk_bf16_f32 v101, v104, v105
	v_lshl_add_u64 v[102:103], v[102:103], 0, v[116:117]
	global_store_dwordx4 v[102:103], v[98:101], off sc0 sc1
	ds_read2_b32 v[98:99], v150 offset0:32 offset1:48
	s_waitcnt lgkmcnt(0)
	v_pk_mul_f32 v[94:95], v[94:95], v[98:99] op_sel_hi:[1,0]
	s_nop 0
	v_pk_mul_f32 v[100:101], v[94:95], v[244:245]
	v_exp_f32_e32 v100, v100
	v_exp_f32_e32 v101, v101
	v_pk_mul_f32 v[90:91], v[90:91], v[98:99] op_sel_hi:[1,0]
	v_pk_mul_f32 v[92:93], v[92:93], v[98:99] op_sel_hi:[1,0]
	v_pk_add_f32 v[100:101], v[100:101], v[246:247]
	v_rcp_f32_e32 v100, v100
	v_rcp_f32_e32 v101, v101
	v_pk_mul_f32 v[86:87], v[86:87], v[98:99] op_sel_hi:[1,0]
	v_pk_mul_f32 v[82:83], v[82:83], v[98:99] op_sel_hi:[1,0]
	v_pk_mul_f32 v[84:85], v[84:85], v[98:99] op_sel_hi:[1,0]
	v_pk_mul_f32 v[94:95], v[94:95], v[100:101]
	s_nop 0
	v_pk_mul_f32 v[90:91], v[90:91], v[94:95]
	v_pk_mul_f32 v[94:95], v[96:97], v[98:99] op_sel_hi:[1,0]
	s_nop 0
	v_pk_mul_f32 v[96:97], v[94:95], v[244:245]
	v_exp_f32_e32 v96, v96
	v_exp_f32_e32 v97, v97
	s_nop 0
	v_pk_add_f32 v[96:97], v[96:97], v[246:247]
	v_rcp_f32_e32 v96, v96
	v_rcp_f32_e32 v97, v97
	s_nop 0
	v_pk_mul_f32 v[94:95], v[94:95], v[96:97]
	s_nop 0
	v_pk_mul_f32 v[92:93], v[92:93], v[94:95]
	v_pk_mul_f32 v[94:95], v[86:87], v[244:245]
	v_exp_f32_e32 v94, v94
	v_exp_f32_e32 v95, v95
	s_nop 0
	v_pk_add_f32 v[94:95], v[94:95], v[246:247]
	v_rcp_f32_e32 v94, v94
	v_rcp_f32_e32 v95, v95
	s_nop 0
	v_pk_mul_f32 v[86:87], v[86:87], v[94:95]
	s_nop 0
	v_pk_mul_f32 v[86:87], v[82:83], v[86:87]
	v_pk_mul_f32 v[82:83], v[88:89], v[98:99] op_sel_hi:[1,0]
	v_or_b32_e32 v94, 32, v149
	v_pk_mul_f32 v[88:89], v[82:83], v[244:245]
	v_exp_f32_e32 v88, v88
	v_exp_f32_e32 v89, v89
	s_nop 0
	v_pk_add_f32 v[88:89], v[88:89], v[246:247]
	v_rcp_f32_e32 v88, v88
	v_rcp_f32_e32 v89, v89
	s_nop 0
	v_pk_mul_f32 v[82:83], v[82:83], v[88:89]
	s_nop 0
	v_pk_mul_f32 v[88:89], v[84:85], v[82:83]
	v_cvt_pk_bf16_f32 v84, v86, v87
	v_mad_i64_i32 v[86:87], s[30:31], v94, s15, v[114:115]
	v_cvt_pk_bf16_f32 v82, v90, v91
	v_cvt_pk_bf16_f32 v83, v92, v93
	v_cvt_pk_bf16_f32 v85, v88, v89
	v_lshl_add_u64 v[86:87], v[86:87], 0, v[116:117]
	global_store_dwordx4 v[86:87], v[82:85], off sc0 sc1
	s_nop 1
	v_mov_b32_e32 v82, v99
	v_pk_mul_f32 v[78:79], v[78:79], v[82:83] op_sel_hi:[1,0]
	s_nop 0
	v_mul_f32_e32 v83, 0xbfb8aa3b, v78
	v_exp_f32_e32 v83, v83
	s_nop 0
	v_add_f32_e32 v83, 1.0, v83
	v_rcp_f32_e32 v84, v83
	v_pk_mul_f32 v[74:75], v[74:75], v[82:83] op_sel_hi:[1,0]
	v_mul_f32_e32 v83, 0xbfb8aa3b, v79
	v_exp_f32_e32 v83, v83
	s_nop 0
	v_add_f32_e32 v83, 1.0, v83
	v_rcp_f32_e32 v85, v83
	v_pk_mul_f32 v[76:77], v[76:77], v[82:83] op_sel_hi:[1,0]
	v_pk_mul_f32 v[70:71], v[70:71], v[82:83] op_sel_hi:[1,0]
	v_pk_mul_f32 v[66:67], v[66:67], v[82:83] op_sel_hi:[1,0]
	v_pk_mul_f32 v[78:79], v[78:79], v[84:85]
	v_pk_mul_f32 v[68:69], v[68:69], v[82:83] op_sel_hi:[1,0]
	v_pk_mul_f32 v[74:75], v[74:75], v[78:79]
	v_pk_mul_f32 v[78:79], v[80:81], v[82:83] op_sel_hi:[1,0]
	s_nop 0
	v_pk_mul_f32 v[80:81], v[78:79], v[244:245]
	v_exp_f32_e32 v80, v80
	v_exp_f32_e32 v81, v81
	s_nop 0
	v_pk_add_f32 v[80:81], v[80:81], v[246:247]
	v_rcp_f32_e32 v80, v80
	v_rcp_f32_e32 v81, v81
	s_nop 0
	v_pk_mul_f32 v[78:79], v[78:79], v[80:81]
	s_nop 0
	v_pk_mul_f32 v[76:77], v[76:77], v[78:79]
	v_pk_mul_f32 v[78:79], v[70:71], v[244:245]
	v_exp_f32_e32 v78, v78
	v_exp_f32_e32 v79, v79
	s_nop 0
	v_pk_add_f32 v[78:79], v[78:79], v[246:247]
	v_rcp_f32_e32 v78, v78
	v_rcp_f32_e32 v79, v79
	s_nop 0
	v_pk_mul_f32 v[70:71], v[70:71], v[78:79]
	s_nop 0
	v_pk_mul_f32 v[70:71], v[66:67], v[70:71]
	v_pk_mul_f32 v[66:67], v[72:73], v[82:83] op_sel_hi:[1,0]
	v_or_b32_e32 v78, 48, v149
	v_pk_mul_f32 v[72:73], v[66:67], v[244:245]
	v_exp_f32_e32 v72, v72
	v_exp_f32_e32 v73, v73
	s_nop 0
	v_pk_add_f32 v[72:73], v[72:73], v[246:247]
	v_rcp_f32_e32 v72, v72
	v_rcp_f32_e32 v73, v73
	s_nop 0
	v_pk_mul_f32 v[66:67], v[66:67], v[72:73]
	s_nop 0
	v_pk_mul_f32 v[72:73], v[68:69], v[66:67]
	v_cvt_pk_bf16_f32 v68, v70, v71
	v_mad_i64_i32 v[70:71], s[30:31], v78, s15, v[114:115]
	v_cvt_pk_bf16_f32 v66, v74, v75
	v_cvt_pk_bf16_f32 v67, v76, v77
	v_cvt_pk_bf16_f32 v69, v72, v73
	v_lshl_add_u64 v[70:71], v[70:71], 0, v[116:117]
	global_store_dwordx4 v[70:71], v[66:69], off sc0 sc1
	ds_read2_b32 v[66:67], v150 offset0:128 offset1:144
	v_add_u32_e32 v70, 0x80, v149
	s_waitcnt lgkmcnt(0)
	v_pk_mul_f32 v[62:63], v[62:63], v[66:67] op_sel_hi:[1,0]
	s_nop 0
	v_pk_mul_f32 v[68:69], v[62:63], v[244:245]
	v_exp_f32_e32 v68, v68
	v_exp_f32_e32 v69, v69
	v_pk_mul_f32 v[58:59], v[58:59], v[66:67] op_sel_hi:[1,0]
	v_pk_mul_f32 v[60:61], v[60:61], v[66:67] op_sel_hi:[1,0]
	v_pk_add_f32 v[68:69], v[68:69], v[246:247]
	v_rcp_f32_e32 v68, v68
	v_rcp_f32_e32 v69, v69
	v_pk_mul_f32 v[54:55], v[54:55], v[66:67] op_sel_hi:[1,0]
	v_pk_mul_f32 v[50:51], v[50:51], v[66:67] op_sel_hi:[1,0]
	v_pk_mul_f32 v[52:53], v[52:53], v[66:67] op_sel_hi:[1,0]
	v_pk_mul_f32 v[62:63], v[62:63], v[68:69]
	s_nop 0
	v_pk_mul_f32 v[58:59], v[58:59], v[62:63]
	v_pk_mul_f32 v[62:63], v[64:65], v[66:67] op_sel_hi:[1,0]
	s_nop 0
	v_pk_mul_f32 v[64:65], v[62:63], v[244:245]
	v_exp_f32_e32 v64, v64
	v_exp_f32_e32 v65, v65
	s_nop 0
	v_pk_add_f32 v[64:65], v[64:65], v[246:247]
	v_rcp_f32_e32 v64, v64
	v_rcp_f32_e32 v65, v65
	s_nop 0
	v_pk_mul_f32 v[62:63], v[62:63], v[64:65]
	s_nop 0
	v_pk_mul_f32 v[60:61], v[60:61], v[62:63]
	v_pk_mul_f32 v[62:63], v[54:55], v[244:245]
	v_exp_f32_e32 v62, v62
	v_exp_f32_e32 v63, v63
	s_nop 0
	v_pk_add_f32 v[62:63], v[62:63], v[246:247]
	v_rcp_f32_e32 v62, v62
	v_rcp_f32_e32 v63, v63
	s_nop 0
	v_pk_mul_f32 v[54:55], v[54:55], v[62:63]
	s_nop 0
	v_pk_mul_f32 v[54:55], v[50:51], v[54:55]
	v_pk_mul_f32 v[50:51], v[56:57], v[66:67] op_sel_hi:[1,0]
	s_nop 0
	v_pk_mul_f32 v[56:57], v[50:51], v[244:245]
	v_exp_f32_e32 v56, v56
	v_exp_f32_e32 v57, v57
	s_nop 0
	v_pk_add_f32 v[56:57], v[56:57], v[246:247]
	v_rcp_f32_e32 v56, v56
	v_rcp_f32_e32 v57, v57
	s_nop 0
	v_pk_mul_f32 v[50:51], v[50:51], v[56:57]
	s_nop 0
	v_pk_mul_f32 v[56:57], v[52:53], v[50:51]
	v_cvt_pk_bf16_f32 v52, v54, v55
	v_mad_i64_i32 v[54:55], s[30:31], v70, s15, v[114:115]
	v_cvt_pk_bf16_f32 v50, v58, v59
	v_cvt_pk_bf16_f32 v51, v60, v61
	v_cvt_pk_bf16_f32 v53, v56, v57
	v_lshl_add_u64 v[54:55], v[54:55], 0, v[116:117]
	global_store_dwordx4 v[54:55], v[50:53], off sc0 sc1
	s_nop 1
	v_mov_b32_e32 v50, v67
	v_pk_mul_f32 v[46:47], v[46:47], v[50:51] op_sel_hi:[1,0]
	s_nop 0
	v_mul_f32_e32 v51, 0xbfb8aa3b, v46
	v_exp_f32_e32 v51, v51
	s_nop 0
	v_add_f32_e32 v51, 1.0, v51
	v_rcp_f32_e32 v52, v51
	v_pk_mul_f32 v[42:43], v[42:43], v[50:51] op_sel_hi:[1,0]
	v_mul_f32_e32 v51, 0xbfb8aa3b, v47
	v_exp_f32_e32 v51, v51
	s_nop 0
	v_add_f32_e32 v51, 1.0, v51
	v_rcp_f32_e32 v53, v51
	v_pk_mul_f32 v[44:45], v[44:45], v[50:51] op_sel_hi:[1,0]
	v_pk_mul_f32 v[38:39], v[38:39], v[50:51] op_sel_hi:[1,0]
	v_pk_mul_f32 v[34:35], v[34:35], v[50:51] op_sel_hi:[1,0]
	v_pk_mul_f32 v[46:47], v[46:47], v[52:53]
	v_pk_mul_f32 v[36:37], v[36:37], v[50:51] op_sel_hi:[1,0]
	v_pk_mul_f32 v[42:43], v[42:43], v[46:47]
	v_pk_mul_f32 v[46:47], v[48:49], v[50:51] op_sel_hi:[1,0]
	s_nop 0
	v_pk_mul_f32 v[48:49], v[46:47], v[244:245]
	v_exp_f32_e32 v48, v48
	v_exp_f32_e32 v49, v49
	s_nop 0
	v_pk_add_f32 v[48:49], v[48:49], v[246:247]
	v_rcp_f32_e32 v48, v48
	v_rcp_f32_e32 v49, v49
	s_nop 0
	v_pk_mul_f32 v[46:47], v[46:47], v[48:49]
	s_nop 0
	v_pk_mul_f32 v[44:45], v[44:45], v[46:47]
	v_pk_mul_f32 v[46:47], v[38:39], v[244:245]
	v_exp_f32_e32 v46, v46
	v_exp_f32_e32 v47, v47
	s_nop 0
	v_pk_add_f32 v[46:47], v[46:47], v[246:247]
	v_rcp_f32_e32 v46, v46
	v_rcp_f32_e32 v47, v47
	s_nop 0
	v_pk_mul_f32 v[38:39], v[38:39], v[46:47]
	s_nop 0
	v_pk_mul_f32 v[38:39], v[34:35], v[38:39]
	v_pk_mul_f32 v[34:35], v[40:41], v[50:51] op_sel_hi:[1,0]
	v_add_u32_e32 v46, 0x90, v149
	v_pk_mul_f32 v[40:41], v[34:35], v[244:245]
	v_exp_f32_e32 v40, v40
	v_exp_f32_e32 v41, v41
	s_nop 0
	v_pk_add_f32 v[40:41], v[40:41], v[246:247]
	v_rcp_f32_e32 v40, v40
	v_rcp_f32_e32 v41, v41
	s_nop 0
	v_pk_mul_f32 v[34:35], v[34:35], v[40:41]
	s_nop 0
	v_pk_mul_f32 v[40:41], v[36:37], v[34:35]
	v_cvt_pk_bf16_f32 v36, v38, v39
	v_mad_i64_i32 v[38:39], s[30:31], v46, s15, v[114:115]
	v_cvt_pk_bf16_f32 v34, v42, v43
	v_cvt_pk_bf16_f32 v35, v44, v45
	v_cvt_pk_bf16_f32 v37, v40, v41
	v_lshl_add_u64 v[38:39], v[38:39], 0, v[116:117]
	global_store_dwordx4 v[38:39], v[34:37], off sc0 sc1
	ds_read2_b32 v[34:35], v150 offset0:160 offset1:176
	s_waitcnt lgkmcnt(0)
	v_pk_mul_f32 v[30:31], v[30:31], v[34:35] op_sel_hi:[1,0]
	s_nop 0
	v_pk_mul_f32 v[36:37], v[30:31], v[244:245]
	v_exp_f32_e32 v36, v36
	v_exp_f32_e32 v37, v37
	v_pk_mul_f32 v[26:27], v[26:27], v[34:35] op_sel_hi:[1,0]
	v_pk_mul_f32 v[28:29], v[28:29], v[34:35] op_sel_hi:[1,0]
	v_pk_add_f32 v[36:37], v[36:37], v[246:247]
	v_rcp_f32_e32 v36, v36
	v_rcp_f32_e32 v37, v37
	v_pk_mul_f32 v[22:23], v[22:23], v[34:35] op_sel_hi:[1,0]
	v_pk_mul_f32 v[18:19], v[18:19], v[34:35] op_sel_hi:[1,0]
	v_pk_mul_f32 v[20:21], v[20:21], v[34:35] op_sel_hi:[1,0]
	v_pk_mul_f32 v[30:31], v[30:31], v[36:37]
	s_nop 0
	v_pk_mul_f32 v[26:27], v[26:27], v[30:31]
	v_pk_mul_f32 v[30:31], v[32:33], v[34:35] op_sel_hi:[1,0]
	s_nop 0
	v_pk_mul_f32 v[32:33], v[30:31], v[244:245]
	v_exp_f32_e32 v32, v32
	v_exp_f32_e32 v33, v33
	s_nop 0
	v_pk_add_f32 v[32:33], v[32:33], v[246:247]
	v_rcp_f32_e32 v32, v32
	v_rcp_f32_e32 v33, v33
	s_nop 0
	v_pk_mul_f32 v[30:31], v[30:31], v[32:33]
	s_nop 0
	v_pk_mul_f32 v[28:29], v[28:29], v[30:31]
	v_pk_mul_f32 v[30:31], v[22:23], v[244:245]
	v_exp_f32_e32 v30, v30
	v_exp_f32_e32 v31, v31
	s_nop 0
	v_pk_add_f32 v[30:31], v[30:31], v[246:247]
	v_rcp_f32_e32 v30, v30
	v_rcp_f32_e32 v31, v31
	s_nop 0
	v_pk_mul_f32 v[22:23], v[22:23], v[30:31]
	s_nop 0
	v_pk_mul_f32 v[22:23], v[18:19], v[22:23]
	v_pk_mul_f32 v[18:19], v[24:25], v[34:35] op_sel_hi:[1,0]
	v_add_u32_e32 v30, 0xa0, v149
	v_pk_mul_f32 v[24:25], v[18:19], v[244:245]
	v_exp_f32_e32 v24, v24
	v_exp_f32_e32 v25, v25
	s_nop 0
	v_pk_add_f32 v[24:25], v[24:25], v[246:247]
	v_rcp_f32_e32 v24, v24
	v_rcp_f32_e32 v25, v25
	s_nop 0
	v_pk_mul_f32 v[18:19], v[18:19], v[24:25]
	s_nop 0
	v_pk_mul_f32 v[24:25], v[20:21], v[18:19]
	v_cvt_pk_bf16_f32 v20, v22, v23
	v_mad_i64_i32 v[22:23], s[30:31], v30, s15, v[114:115]
	v_cvt_pk_bf16_f32 v18, v26, v27
	v_cvt_pk_bf16_f32 v19, v28, v29
	v_cvt_pk_bf16_f32 v21, v24, v25
	v_lshl_add_u64 v[22:23], v[22:23], 0, v[116:117]
	global_store_dwordx4 v[22:23], v[18:21], off sc0 sc1
	s_nop 1
	v_mov_b32_e32 v18, v35
	v_pk_mul_f32 v[14:15], v[14:15], v[18:19] op_sel_hi:[1,0]
	s_nop 0
	v_mul_f32_e32 v19, 0xbfb8aa3b, v14
	v_exp_f32_e32 v19, v19
	s_nop 0
	v_add_f32_e32 v19, 1.0, v19
	v_rcp_f32_e32 v20, v19
	v_pk_mul_f32 v[10:11], v[10:11], v[18:19] op_sel_hi:[1,0]
	v_mul_f32_e32 v19, 0xbfb8aa3b, v15
	v_exp_f32_e32 v19, v19
	s_nop 0
	v_add_f32_e32 v19, 1.0, v19
	v_rcp_f32_e32 v21, v19
	v_pk_mul_f32 v[12:13], v[12:13], v[18:19] op_sel_hi:[1,0]
	v_pk_mul_f32 v[6:7], v[6:7], v[18:19] op_sel_hi:[1,0]
	v_pk_mul_f32 v[2:3], v[2:3], v[18:19] op_sel_hi:[1,0]
	v_pk_mul_f32 v[14:15], v[14:15], v[20:21]
	v_pk_mul_f32 v[4:5], v[4:5], v[18:19] op_sel_hi:[1,0]
	v_pk_mul_f32 v[10:11], v[10:11], v[14:15]
	v_pk_mul_f32 v[14:15], v[16:17], v[18:19] op_sel_hi:[1,0]
	s_nop 0
	v_pk_mul_f32 v[16:17], v[14:15], v[244:245]
	v_exp_f32_e32 v16, v16
	v_exp_f32_e32 v17, v17
	s_nop 0
	v_pk_add_f32 v[16:17], v[16:17], v[246:247]
	v_rcp_f32_e32 v16, v16
	v_rcp_f32_e32 v17, v17
	s_nop 0
	v_pk_mul_f32 v[14:15], v[14:15], v[16:17]
	s_nop 0
	v_pk_mul_f32 v[12:13], v[12:13], v[14:15]
	v_pk_mul_f32 v[14:15], v[6:7], v[244:245]
	v_exp_f32_e32 v14, v14
	v_exp_f32_e32 v15, v15
	s_nop 0
	v_pk_add_f32 v[14:15], v[14:15], v[246:247]
	v_rcp_f32_e32 v14, v14
	v_rcp_f32_e32 v15, v15
	s_nop 0
	v_pk_mul_f32 v[6:7], v[6:7], v[14:15]
	s_nop 0
	v_pk_mul_f32 v[6:7], v[2:3], v[6:7]
	v_pk_mul_f32 v[2:3], v[8:9], v[18:19] op_sel_hi:[1,0]
	v_add_u32_e32 v14, 0xb0, v149
	v_pk_mul_f32 v[8:9], v[2:3], v[244:245]
	v_exp_f32_e32 v8, v8
	v_exp_f32_e32 v9, v9
	s_nop 0
	v_pk_add_f32 v[8:9], v[8:9], v[246:247]
	v_rcp_f32_e32 v8, v8
	v_rcp_f32_e32 v9, v9
	s_nop 0
	v_pk_mul_f32 v[2:3], v[2:3], v[8:9]
	s_nop 0
	v_pk_mul_f32 v[8:9], v[4:5], v[2:3]
	v_cvt_pk_bf16_f32 v4, v6, v7
	v_mad_i64_i32 v[6:7], s[30:31], v14, s15, v[114:115]
	v_cvt_pk_bf16_f32 v2, v10, v11
	v_cvt_pk_bf16_f32 v3, v12, v13
	v_cvt_pk_bf16_f32 v5, v8, v9
	v_lshl_add_u64 v[6:7], v[6:7], 0, v[116:117]
	s_mov_b64 s[30:31], -1
	global_store_dwordx4 v[6:7], v[2:5], off sc0 sc1
	s_cbranch_vccnz .LBB0_808
	s_andn2_b64 vcc, exec, s[8:9]
	s_cbranch_vccnz .LBB0_807
	s_barrier
	s_branch .LBB0_807
